# v77 + attention work stealing: one vector read of all eight queue counters marks exhausted queues before the serial steal attempts (end-of-phase scan: up to 7 atomic round trips -> 1 load)
# speedup vs baseline: 1.0037x; 1.0037x over previous
.LBB0_598:
	s_cmp_lg_u32 s6, 1
	s_cbranch_scc1 .Ltk_noscan
	s_mov_b64 s[100:101], exec
	s_mov_b64 exec, 0xff
	v_mbcnt_lo_u32_b32 v22, -1, 0
	v_lshlrev_b32_e32 v22, 7, v22
	global_load_dword v23, v22, s[8:9] sc1
	s_waitcnt vmcnt(0)
	v_cmp_lt_u32_e32 vcc, 0x81, v23
	s_and_b32 s99, vcc_lo, 0xff
	s_mov_b64 exec, s[100:101]
	v_or_b32_e32 v221, s99, v221
